# even_c: swapped roles - blocks < 256 defer the G2 scan, blocks >= 256 (prio 1) scan first
# speedup vs baseline: 1.0002x; 1.0002x over previous
; DI void phase_even_c(const Ctx& c, int l, bf16* lds) {
;   gla_g2(c);
;   xcd_items(512, [&](int it) { attn_item(c, it, lds); });
; }
.Lg2_entry:
	v_readlane_b32 s2, v252, 32
	v_readlane_b32 s3, v255, 4
	s_cmp_ge_u32 s2, 0x10000
	s_cbranch_scc1 .Lg2_go
	s_cmp_eq_u32 s3, 2
	s_cbranch_scc1 .Lg2_go
	s_mov_b32 s3, 1
	s_nop 0
	v_writelane_b32 v255, s3, 4
	s_branch .LBB0_799
